# RG-LRU unit: the four z-gate loads are issued right after the carry-in fold instead of after the scan barrier; final sample-row LayerNorm: gamma/beta loads of all four column blocks issued together; o
# baseline (speedup 1.0000x reference)
.LBB0_406:
	s_or_b64 exec, exec, s[14:15]
	s_lshl_b32 s14, s22, 13
	s_add_i32 s14, s14, s51
	v_add_u32_e32 v34, s14, v111
	v_ashrrev_i32_e32 v35, 31, v34
	v_lshlrev_b64 v[36:37], 12, v[34:35]
	v_add_u32_e32 v40, s14, v159
	v_lshl_add_u64 v[36:37], v[104:105], 0, v[36:37]
	v_ashrrev_i32_e32 v41, 31, v40
	s_waitcnt lgkmcnt(0)
	s_barrier
	s_waitcnt vmcnt(0)
	v_mov_b64_e32 v[44:45], v[222:223]
	v_mov_b64_e32 v[46:47], v[224:225]
	v_lshlrev_b64 v[36:37], 12, v[40:41]
	v_lshl_add_u64 v[36:37], v[104:105], 0, v[36:37]
	v_mov_b64_e32 v[48:49], v[226:227]
	v_mov_b64_e32 v[50:51], v[228:229]
	v_add_u32_e32 v42, s14, v160
	v_add_u32_e32 v38, s14, v161
	v_ashrrev_i32_e32 v43, 31, v42
	v_ashrrev_i32_e32 v39, 31, v38
	v_lshlrev_b64 v[36:37], 12, v[42:43]
	v_lshlrev_b64 v[68:69], 12, v[38:39]
	v_lshlrev_b64 v[34:35], 11, v[34:35]
	v_lshl_add_u64 v[36:37], v[104:105], 0, v[36:37]
	ds_read_b128 v[52:55], v168 offset:34816
	ds_read_b128 v[56:59], v168 offset:34832
	ds_read_b128 v[60:63], v169 offset:34816
	ds_read_b128 v[64:67], v169 offset:34832
	v_lshl_add_u64 v[72:73], v[104:105], 0, v[68:69]
	v_lshl_add_u64 v[74:75], v[102:103], 0, v[34:35]
	v_mov_b64_e32 v[68:69], v[230:231]
	v_mov_b64_e32 v[70:71], v[232:233]
	s_nop 0
	v_mov_b64_e32 v[34:35], v[234:235]
	v_mov_b64_e32 v[36:37], v[236:237]
	v_lshlrev_b64 v[40:41], 11, v[40:41]
	v_lshl_add_u64 v[40:41], v[102:103], 0, v[40:41]
	v_lshlrev_b64 v[38:39], 11, v[38:39]
	s_add_i32 s50, s50, s74
	v_lshl_add_u64 v[38:39], v[102:103], 0, v[38:39]
	s_cmpk_gt_i32 s50, 0x3ff
	s_waitcnt vmcnt(3)
	v_lshlrev_b32_e32 v72, 16, v44
	v_and_b32_e32 v73, 0xffff0000, v44
	v_lshlrev_b32_e32 v44, 16, v45
	v_and_b32_e32 v45, 0xffff0000, v45
	v_lshlrev_b32_e32 v76, 16, v46
	v_and_b32_e32 v77, 0xffff0000, v46
	v_lshlrev_b32_e32 v46, 16, v47
	v_and_b32_e32 v47, 0xffff0000, v47
	s_waitcnt vmcnt(2)
	v_lshlrev_b32_e32 v78, 16, v48
	v_and_b32_e32 v79, 0xffff0000, v48
	v_mul_f32_e32 v80, 0xbfb8aa3b, v72
	s_waitcnt lgkmcnt(3)
	v_pk_mul_f32 v[52:53], v[52:53], v[72:73]
	v_mul_f32_e32 v72, 0xbfb8aa3b, v73
	v_mul_f32_e32 v73, 0xbfb8aa3b, v44
	v_pk_mul_f32 v[54:55], v[54:55], v[44:45]
	v_mul_f32_e32 v81, 0xbfb8aa3b, v45
	v_mul_f32_e32 v88, 0xbfb8aa3b, v76
	s_waitcnt lgkmcnt(2)
	v_pk_mul_f32 v[44:45], v[56:57], v[76:77]
	v_mul_f32_e32 v76, 0xbfb8aa3b, v77
	v_mul_f32_e32 v77, 0xbfb8aa3b, v46
	v_pk_mul_f32 v[56:57], v[58:59], v[46:47]
	v_mul_f32_e32 v46, 0xbfb8aa3b, v47
	v_mul_f32_e32 v47, 0xbfb8aa3b, v78
	s_waitcnt lgkmcnt(1)
	v_pk_mul_f32 v[58:59], v[60:61], v[78:79]
	v_mul_f32_e32 v60, 0xbfb8aa3b, v79
	v_exp_f32_e32 v79, v80
	v_exp_f32_e32 v72, v72
	v_exp_f32_e32 v73, v73
	v_exp_f32_e32 v80, v81
	v_exp_f32_e32 v81, v88
	v_exp_f32_e32 v76, v76
	v_exp_f32_e32 v77, v77
	v_exp_f32_e32 v46, v46
	v_exp_f32_e32 v47, v47
	v_exp_f32_e32 v60, v60
	v_lshlrev_b32_e32 v48, 16, v49
	v_and_b32_e32 v49, 0xffff0000, v49
	v_mul_f32_e32 v61, 0xbfb8aa3b, v48
	v_mul_f32_e32 v78, 0xbfb8aa3b, v49
	v_exp_f32_e32 v88, v61
	v_exp_f32_e32 v107, v78
	v_add_f32_e32 v61, 1.0, v79
	v_add_f32_e32 v72, 1.0, v72
	v_add_f32_e32 v73, 1.0, v73
	v_add_f32_e32 v78, 1.0, v80
	v_add_f32_e32 v79, 1.0, v81
	v_add_f32_e32 v76, 1.0, v76
	v_add_f32_e32 v77, 1.0, v77
	v_add_f32_e32 v80, 1.0, v46
	v_add_f32_e32 v81, 1.0, v47
	v_add_f32_e32 v172, 1.0, v60
	v_rcp_f32_e32 v46, v61
	v_rcp_f32_e32 v47, v72
	v_rcp_f32_e32 v60, v73
	v_rcp_f32_e32 v61, v78
	v_rcp_f32_e32 v72, v79
	v_rcp_f32_e32 v73, v76
	v_rcp_f32_e32 v76, v77
	v_rcp_f32_e32 v77, v80
	v_pk_mul_f32 v[46:47], v[52:53], v[46:47]
	v_pk_mul_f32 v[52:53], v[54:55], v[60:61]
	v_pk_mul_f32 v[54:55], v[44:45], v[72:73]
	v_pk_mul_f32 v[56:57], v[56:57], v[76:77]
	v_cvt_pk_bf16_f32 v44, v46, v47
	v_cvt_pk_bf16_f32 v45, v52, v53
	v_cvt_pk_bf16_f32 v46, v54, v55
	v_cvt_pk_bf16_f32 v47, v56, v57
	global_store_dwordx4 v[74:75], v[44:47], off
	v_rcp_f32_e32 v78, v81
	v_rcp_f32_e32 v79, v172
	v_add_f32_e32 v44, 1.0, v88
	v_rcp_f32_e32 v46, v44
	v_add_f32_e32 v44, 1.0, v107
	v_rcp_f32_e32 v47, v44
	v_pk_mul_f32 v[48:49], v[62:63], v[48:49]
	v_pk_mul_f32 v[44:45], v[78:79], v[58:59]
	s_waitcnt vmcnt(2)
	v_lshlrev_b32_e32 v54, 16, v69
	v_pk_mul_f32 v[46:47], v[46:47], v[48:49]
	v_cvt_pk_bf16_f32 v44, v44, v45
	v_cvt_pk_bf16_f32 v45, v46, v47
	v_lshlrev_b32_e32 v46, 16, v50
	v_mul_f32_e32 v47, 0xbfb8aa3b, v46
	v_exp_f32_e32 v48, v47
	v_and_b32_e32 v47, 0xffff0000, v50
	v_mul_f32_e32 v49, 0xbfb8aa3b, v47
	v_lshlrev_b32_e32 v50, 16, v51
	v_and_b32_e32 v51, 0xffff0000, v51
	v_exp_f32_e32 v49, v49
	v_mul_f32_e32 v52, 0xbfb8aa3b, v50
	v_mul_f32_e32 v53, 0xbfb8aa3b, v51
	v_exp_f32_e32 v52, v52
	v_exp_f32_e32 v53, v53
	v_add_f32_e32 v48, 1.0, v48
	v_add_f32_e32 v49, 1.0, v49
	v_rcp_f32_e32 v48, v48
	v_rcp_f32_e32 v49, v49
	v_add_f32_e32 v52, 1.0, v52
	v_add_f32_e32 v53, 1.0, v53
	v_rcp_f32_e32 v52, v52
	v_rcp_f32_e32 v53, v53
	s_waitcnt lgkmcnt(0)
	v_pk_mul_f32 v[46:47], v[64:65], v[46:47]
	v_and_b32_e32 v55, 0xffff0000, v69
	v_pk_mul_f32 v[46:47], v[48:49], v[46:47]
	v_pk_mul_f32 v[48:49], v[66:67], v[50:51]
	v_cvt_pk_bf16_f32 v46, v46, v47
	v_pk_mul_f32 v[48:49], v[52:53], v[48:49]
	s_nop 0
	v_cvt_pk_bf16_f32 v47, v48, v49
	global_store_dwordx4 v[40:41], v[44:47], off
	v_lshlrev_b32_e32 v40, 16, v68
	v_mul_f32_e32 v41, 0xbfb8aa3b, v40
	v_exp_f32_e32 v52, v41
	v_and_b32_e32 v41, 0xffff0000, v68
	ds_read_b128 v[44:47], v170 offset:34816
	ds_read_b128 v[48:51], v170 offset:34832
	v_mul_f32_e32 v53, 0xbfb8aa3b, v41
	v_exp_f32_e32 v53, v53
	v_add_f32_e32 v52, 1.0, v52
	s_waitcnt lgkmcnt(1)
	v_pk_mul_f32 v[40:41], v[44:45], v[40:41]
	v_mul_f32_e32 v45, 0xbfb8aa3b, v54
	v_add_f32_e32 v44, 1.0, v53
	v_exp_f32_e32 v45, v45
	v_mul_f32_e32 v53, 0xbfb8aa3b, v55
	v_exp_f32_e32 v57, v53
	v_rcp_f32_e32 v52, v52
	v_rcp_f32_e32 v53, v44
	v_add_f32_e32 v44, 1.0, v45
	v_rcp_f32_e32 v56, v44
	v_add_f32_e32 v44, 1.0, v57
	v_rcp_f32_e32 v57, v44
	v_pk_mul_f32 v[40:41], v[52:53], v[40:41]
	s_nop 0
	v_cvt_pk_bf16_f32 v44, v40, v41
	v_pk_mul_f32 v[40:41], v[46:47], v[54:55]
	s_nop 0
	v_pk_mul_f32 v[40:41], v[56:57], v[40:41]
	s_nop 0
	v_cvt_pk_bf16_f32 v45, v40, v41
	v_lshlrev_b32_e32 v40, 16, v70
	v_mul_f32_e32 v41, 0xbfb8aa3b, v40
	v_exp_f32_e32 v46, v41
	v_and_b32_e32 v41, 0xffff0000, v70
	v_mul_f32_e32 v47, 0xbfb8aa3b, v41
	v_exp_f32_e32 v47, v47
	s_waitcnt lgkmcnt(0)
	v_pk_mul_f32 v[40:41], v[48:49], v[40:41]
	v_lshlrev_b32_e32 v48, 16, v71
	v_and_b32_e32 v49, 0xffff0000, v71
	v_mul_f32_e32 v52, 0xbfb8aa3b, v48
	v_mul_f32_e32 v53, 0xbfb8aa3b, v49
	v_exp_f32_e32 v52, v52
	v_exp_f32_e32 v53, v53
	v_add_f32_e32 v46, 1.0, v46
	v_add_f32_e32 v47, 1.0, v47
	v_rcp_f32_e32 v46, v46
	v_rcp_f32_e32 v47, v47
	v_add_f32_e32 v52, 1.0, v52
	v_add_f32_e32 v53, 1.0, v53
	v_rcp_f32_e32 v52, v52
	v_rcp_f32_e32 v53, v53
	v_pk_mul_f32 v[40:41], v[46:47], v[40:41]
	s_nop 0
	v_cvt_pk_bf16_f32 v46, v40, v41
	v_pk_mul_f32 v[40:41], v[50:51], v[48:49]
	s_waitcnt vmcnt(2)
	v_lshlrev_b32_e32 v48, 16, v34
	v_pk_mul_f32 v[40:41], v[52:53], v[40:41]
	v_mul_f32_e32 v49, 0xbfb8aa3b, v48
	v_cvt_pk_bf16_f32 v47, v40, v41
	v_lshlrev_b64 v[40:41], 11, v[42:43]
	v_lshl_add_u64 v[40:41], v[102:103], 0, v[40:41]
	global_store_dwordx4 v[40:41], v[44:47], off
	ds_read_b128 v[40:43], v171 offset:34816
	ds_read_b128 v[44:47], v171 offset:34832
	v_exp_f32_e32 v50, v49
	v_and_b32_e32 v49, 0xffff0000, v34
	v_mul_f32_e32 v34, 0xbfb8aa3b, v49
	v_exp_f32_e32 v51, v34
	s_waitcnt lgkmcnt(1)
	v_pk_mul_f32 v[40:41], v[40:41], v[48:49]
	v_lshlrev_b32_e32 v48, 16, v35
	v_and_b32_e32 v49, 0xffff0000, v35
	v_mul_f32_e32 v35, 0xbfb8aa3b, v48
	v_add_f32_e32 v34, 1.0, v50
	v_add_f32_e32 v50, 1.0, v51
	v_exp_f32_e32 v51, v35
	v_mul_f32_e32 v35, 0xbfb8aa3b, v49
	v_exp_f32_e32 v52, v35
	v_rcp_f32_e32 v34, v34
	v_rcp_f32_e32 v35, v50
	v_add_f32_e32 v50, 1.0, v51
	v_add_f32_e32 v51, 1.0, v52
	v_rcp_f32_e32 v50, v50
	v_rcp_f32_e32 v51, v51
	v_pk_mul_f32 v[34:35], v[34:35], v[40:41]
	v_pk_mul_f32 v[40:41], v[42:43], v[48:49]
	v_cvt_pk_bf16_f32 v34, v34, v35
	v_pk_mul_f32 v[40:41], v[50:51], v[40:41]
	s_nop 0
	v_cvt_pk_bf16_f32 v35, v40, v41
	v_lshlrev_b32_e32 v40, 16, v36
	v_mul_f32_e32 v41, 0xbfb8aa3b, v40
	v_exp_f32_e32 v42, v41
	v_and_b32_e32 v41, 0xffff0000, v36
	v_mul_f32_e32 v36, 0xbfb8aa3b, v41
	v_exp_f32_e32 v43, v36
	v_add_f32_e32 v36, 1.0, v42
	v_lshlrev_b32_e32 v42, 16, v37
	s_waitcnt lgkmcnt(0)
	v_pk_mul_f32 v[40:41], v[44:45], v[40:41]
	v_add_f32_e32 v44, 1.0, v43
	v_and_b32_e32 v43, 0xffff0000, v37
	v_mul_f32_e32 v37, 0xbfb8aa3b, v42
	v_exp_f32_e32 v45, v37
	v_mul_f32_e32 v37, 0xbfb8aa3b, v43
	v_exp_f32_e32 v48, v37
	v_rcp_f32_e32 v36, v36
	v_rcp_f32_e32 v37, v44
	v_add_f32_e32 v44, 1.0, v45
	v_add_f32_e32 v45, 1.0, v48
	v_rcp_f32_e32 v44, v44
	v_rcp_f32_e32 v45, v45
	v_pk_mul_f32 v[36:37], v[36:37], v[40:41]
	v_pk_mul_f32 v[40:41], v[46:47], v[42:43]
	v_cvt_pk_bf16_f32 v36, v36, v37
	v_pk_mul_f32 v[40:41], v[44:45], v[40:41]
	s_nop 0
	v_cvt_pk_bf16_f32 v37, v40, v41
	global_store_dwordx4 v[38:39], v[34:37], off
	s_barrier
	s_cbranch_scc1 .LBB0_426

.LBB0_424:
	v_cndmask_b32_e64 v216, v212, 0, s[0:1]
	v_cndmask_b32_e64 v34, v209, 1.0, s[0:1]
	v_mul_f32_e32 v217, v34, v206
	v_fmac_f32_e32 v216, v205, v34
	v_cndmask_b32_e64 v214, v214, 0, s[0:1]
	v_cndmask_b32_e64 v34, v213, 1.0, s[0:1]
	v_mul_f32_e32 v215, v210, v34
	v_fmac_f32_e32 v214, v208, v34
	v_cndmask_b32_e64 v212, v225, 0, s[0:1]
	v_cndmask_b32_e64 v34, v222, 1.0, s[0:1]
	v_mul_f32_e32 v213, v220, v34
	v_fmac_f32_e32 v212, v211, v34
	v_cndmask_b32_e64 v210, v227, 0, s[0:1]
	v_cndmask_b32_e64 v34, v226, 1.0, s[0:1]
	v_mul_f32_e32 v211, v223, v34
	v_fmac_f32_e32 v210, v221, v34
	v_cndmask_b32_e64 v208, v230, 0, s[0:1]
	v_cndmask_b32_e64 v34, v229, 1.0, s[0:1]
	v_mul_f32_e32 v209, v228, v34
	v_fmac_f32_e32 v208, v224, v34
	v_cndmask_b32_e64 v206, v234, 0, s[0:1]
	v_cndmask_b32_e64 v34, v232, 1.0, s[0:1]
	v_cmp_gt_i32_e32 vcc, s24, v115
	v_cndmask_b32_e64 v218, v207, 0, s[0:1]
	v_cndmask_b32_e64 v219, v88, 1.0, s[0:1]
	v_mul_f32_e32 v207, v238, v34
	v_fmac_f32_e32 v206, v231, v34
	v_cndmask_b32_e64 v107, v236, 0, s[0:1]
	v_cndmask_b32_e64 v34, v235, 1.0, s[0:1]
	s_lshl_b64 s[14:15], s[22:23], 19
	v_cndmask_b32_e32 v88, 0, v126, vcc
	v_mul_f32_e32 v205, v237, v34
	v_fmac_f32_e32 v107, v233, v34
	v_lshl_add_u64 v[34:35], v[86:87], 0, s[14:15]
	v_lshlrev_b32_e32 v88, 3, v88
	v_lshl_add_u64 v[220:221], v[34:35], 0, v[88:89]
	v_cmp_gt_i32_e32 vcc, s24, v127
	s_nop 1
	v_cndmask_b32_e32 v88, 0, v128, vcc
	v_cmp_gt_i32_e32 vcc, s24, v129
	v_lshlrev_b32_e32 v88, 3, v88
	v_lshl_add_u64 v[222:223], v[34:35], 0, v[88:89]
	v_cndmask_b32_e32 v88, 0, v130, vcc
	v_cmp_gt_i32_e32 vcc, s24, v131
	v_lshlrev_b32_e32 v88, 3, v88
	v_lshl_add_u64 v[224:225], v[34:35], 0, v[88:89]
	v_cndmask_b32_e32 v88, 0, v132, vcc
	v_cmp_gt_i32_e32 vcc, s24, v133
	v_lshlrev_b32_e32 v88, 3, v88
	v_lshl_add_u64 v[226:227], v[34:35], 0, v[88:89]
	v_cndmask_b32_e32 v88, 0, v134, vcc
	v_cmp_gt_i32_e32 vcc, s24, v135
	v_lshlrev_b32_e32 v88, 3, v88
	v_lshl_add_u64 v[228:229], v[34:35], 0, v[88:89]
	v_cndmask_b32_e32 v88, 0, v136, vcc
	v_cmp_gt_i32_e32 vcc, s24, v137
	v_lshlrev_b32_e32 v88, 3, v88
	v_lshl_add_u64 v[230:231], v[34:35], 0, v[88:89]
	v_cndmask_b32_e32 v88, 0, v138, vcc
	v_cmp_gt_i32_e32 vcc, s24, v139
	v_lshlrev_b32_e32 v88, 3, v88
	v_lshl_add_u64 v[232:233], v[34:35], 0, v[88:89]
	v_cndmask_b32_e32 v88, 0, v140, vcc
	v_cmp_gt_i32_e32 vcc, s24, v141
	v_lshlrev_b32_e32 v88, 3, v88
	v_lshl_add_u64 v[234:235], v[34:35], 0, v[88:89]
	v_cndmask_b32_e32 v88, 0, v142, vcc
	v_cmp_gt_i32_e32 vcc, s24, v143
	v_lshlrev_b32_e32 v88, 3, v88
	v_lshl_add_u64 v[236:237], v[34:35], 0, v[88:89]
	v_cndmask_b32_e32 v88, 0, v144, vcc
	v_cmp_gt_i32_e32 vcc, s24, v145
	v_lshlrev_b32_e32 v88, 3, v88
	v_lshl_add_u64 v[238:239], v[34:35], 0, v[88:89]
	v_cndmask_b32_e32 v88, 0, v146, vcc
	v_cmp_gt_i32_e32 vcc, s24, v147
	v_lshlrev_b32_e32 v88, 3, v88
	v_lshl_add_u64 v[242:243], v[34:35], 0, v[88:89]
	v_cndmask_b32_e32 v88, 0, v148, vcc
	v_cmp_gt_i32_e32 vcc, s24, v149
	v_lshlrev_b32_e32 v88, 3, v88
	v_lshl_add_u64 v[244:245], v[34:35], 0, v[88:89]
	v_cndmask_b32_e32 v88, 0, v150, vcc
	v_cmp_gt_i32_e32 vcc, s24, v151
	v_lshlrev_b32_e32 v88, 3, v88
	v_lshl_add_u64 v[246:247], v[34:35], 0, v[88:89]
	v_cndmask_b32_e32 v88, 0, v152, vcc
	v_cmp_gt_i32_e32 vcc, s24, v153
	v_lshlrev_b32_e32 v88, 3, v88
	v_lshl_add_u64 v[248:249], v[34:35], 0, v[88:89]
	v_cndmask_b32_e32 v88, 0, v154, vcc
	v_cmp_gt_i32_e32 vcc, s24, v155
	v_lshlrev_b32_e32 v88, 3, v88
	v_lshl_add_u64 v[250:251], v[34:35], 0, v[88:89]
	v_cndmask_b32_e32 v88, 0, v156, vcc
	v_lshlrev_b32_e32 v88, 3, v88
	v_lshl_add_u64 v[34:35], v[34:35], 0, v[88:89]
	s_waitcnt lgkmcnt(0)
	s_barrier
	global_load_dwordx2 v[220:221], v[220:221], off sc1
	global_load_dwordx2 v[222:223], v[222:223], off sc1
	global_load_dwordx2 v[224:225], v[224:225], off sc1
	global_load_dwordx2 v[226:227], v[226:227], off sc1
	global_load_dwordx2 v[228:229], v[228:229], off sc1
	global_load_dwordx2 v[230:231], v[230:231], off sc1
	global_load_dwordx2 v[232:233], v[232:233], off sc1
	global_load_dwordx2 v[234:235], v[234:235], off sc1
	global_load_dwordx2 v[236:237], v[236:237], off sc1
	global_load_dwordx2 v[238:239], v[238:239], off sc1
	global_load_dwordx2 v[242:243], v[242:243], off sc1
	global_load_dwordx2 v[244:245], v[244:245], off sc1
	global_load_dwordx2 v[246:247], v[246:247], off sc1
	global_load_dwordx2 v[248:249], v[248:249], off sc1
	global_load_dwordx2 v[250:251], v[250:251], off sc1
	global_load_dwordx2 v[34:35], v[34:35], off sc1
	v_fmac_f32_e32 v218, 0, v219
	s_cmp_eq_u32 s24, 63
	s_cselect_b64 s[14:15], -1, 0
	v_cmp_gt_i32_e32 vcc, s24, v115
	s_waitcnt vmcnt(15)
	s_nop 1
	v_cndmask_b32_e32 v220, 1.0, v220, vcc
	v_cndmask_b32_e32 v221, 0, v221, vcc
	v_cmp_gt_i32_e32 vcc, s24, v127
	v_fmac_f32_e32 v221, 0, v220
	s_nop 0
	s_waitcnt vmcnt(14)
	v_cndmask_b32_e32 v222, 1.0, v222, vcc
	v_cndmask_b32_e32 v223, 0, v223, vcc
	v_cmp_gt_i32_e32 vcc, s24, v129
	v_fmac_f32_e32 v223, v222, v221
	v_mul_f32_e32 v222, v220, v222
	s_waitcnt vmcnt(13)
	v_cndmask_b32_e32 v224, 1.0, v224, vcc
	v_cndmask_b32_e32 v225, 0, v225, vcc
	v_cmp_gt_i32_e32 vcc, s24, v131
	v_fmac_f32_e32 v225, v224, v223
	v_mul_f32_e32 v224, v222, v224
	s_waitcnt vmcnt(12)
	v_cndmask_b32_e32 v226, 1.0, v226, vcc
	v_cndmask_b32_e32 v227, 0, v227, vcc
	v_cmp_gt_i32_e32 vcc, s24, v133
	v_fmac_f32_e32 v227, v226, v225
	v_mul_f32_e32 v226, v224, v226
	s_waitcnt vmcnt(11)
	v_cndmask_b32_e32 v228, 1.0, v228, vcc
	v_cndmask_b32_e32 v229, 0, v229, vcc
	v_cmp_gt_i32_e32 vcc, s24, v135
	v_fmac_f32_e32 v229, v228, v227
	v_mul_f32_e32 v228, v226, v228
	s_waitcnt vmcnt(10)
	v_cndmask_b32_e32 v230, 1.0, v230, vcc
	v_cndmask_b32_e32 v231, 0, v231, vcc
	v_cmp_gt_i32_e32 vcc, s24, v137
	v_fmac_f32_e32 v231, v230, v229
	v_mul_f32_e32 v230, v228, v230
	s_waitcnt vmcnt(9)
	v_cndmask_b32_e32 v232, 1.0, v232, vcc
	v_cndmask_b32_e32 v233, 0, v233, vcc
	v_cmp_gt_i32_e32 vcc, s24, v139
	v_fmac_f32_e32 v233, v232, v231
	v_mul_f32_e32 v232, v230, v232
	s_waitcnt vmcnt(8)
	v_cndmask_b32_e32 v234, 1.0, v234, vcc
	v_cndmask_b32_e32 v235, 0, v235, vcc
	v_cmp_gt_i32_e32 vcc, s24, v141
	v_fmac_f32_e32 v235, v234, v233
	v_mul_f32_e32 v234, v232, v234
	s_waitcnt vmcnt(7)
	v_cndmask_b32_e32 v236, 1.0, v236, vcc
	v_cndmask_b32_e32 v237, 0, v237, vcc
	v_cmp_gt_i32_e32 vcc, s24, v143
	v_fmac_f32_e32 v237, v236, v235
	v_mul_f32_e32 v236, v234, v236
	s_waitcnt vmcnt(6)
	v_cndmask_b32_e32 v238, 1.0, v238, vcc
	v_cndmask_b32_e32 v239, 0, v239, vcc
	v_cmp_gt_i32_e32 vcc, s24, v145
	v_fmac_f32_e32 v239, v238, v237
	v_mul_f32_e32 v238, v236, v238
	s_waitcnt vmcnt(5)
	v_cndmask_b32_e32 v242, 1.0, v242, vcc
	v_cndmask_b32_e32 v243, 0, v243, vcc
	v_cmp_gt_i32_e32 vcc, s24, v147
	v_fmac_f32_e32 v243, v242, v239
	v_mul_f32_e32 v242, v238, v242
	s_waitcnt vmcnt(4)
	v_cndmask_b32_e32 v244, 1.0, v244, vcc
	v_cndmask_b32_e32 v245, 0, v245, vcc
	v_cmp_gt_i32_e32 vcc, s24, v149
	v_fmac_f32_e32 v245, v244, v243
	v_mul_f32_e32 v244, v242, v244
	s_waitcnt vmcnt(3)
	v_cndmask_b32_e32 v246, 1.0, v246, vcc
	v_cndmask_b32_e32 v247, 0, v247, vcc
	v_cmp_gt_i32_e32 vcc, s24, v151
	v_fmac_f32_e32 v247, v246, v245
	v_mul_f32_e32 v246, v244, v246
	s_waitcnt vmcnt(2)
	v_cndmask_b32_e32 v248, 1.0, v248, vcc
	v_cndmask_b32_e32 v249, 0, v249, vcc
	v_cmp_gt_i32_e32 vcc, s24, v153
	v_fmac_f32_e32 v249, v248, v247
	v_mul_f32_e32 v248, v246, v248
	s_waitcnt vmcnt(1)
	v_cndmask_b32_e32 v250, 1.0, v250, vcc
	v_cndmask_b32_e32 v251, 0, v251, vcc
	v_cmp_gt_i32_e32 vcc, s24, v155
	v_fmac_f32_e32 v251, v250, v249
	v_mul_f32_e32 v250, v248, v250
	s_waitcnt vmcnt(0)
	v_cndmask_b32_e32 v34, 1.0, v34, vcc
	v_cndmask_b32_e32 v35, 0, v35, vcc
	v_fmac_f32_e32 v35, v34, v251
	v_mul_f32_e32 v34, v250, v34
	s_and_b64 s[24:25], s[6:7], s[14:15]
	s_lshl_b32 s98, s22, 13
	s_add_i32 s98, s98, s51
	v_add_u32_e32 v238, s98, v111
	v_ashrrev_i32_e32 v239, 31, v238
	v_lshlrev_b64 v[238:239], 12, v[238:239]
	v_lshl_add_u64 v[238:239], v[104:105], 0, v[238:239]
	global_load_dwordx4 v[222:225], v[238:239], off offset:2048
	v_add_u32_e32 v242, s98, v159
	v_ashrrev_i32_e32 v243, 31, v242
	v_lshlrev_b64 v[242:243], 12, v[242:243]
	v_lshl_add_u64 v[242:243], v[104:105], 0, v[242:243]
	global_load_dwordx4 v[226:229], v[242:243], off offset:2048
	v_add_u32_e32 v244, s98, v160
	v_ashrrev_i32_e32 v245, 31, v244
	v_lshlrev_b64 v[244:245], 12, v[244:245]
	v_lshl_add_u64 v[244:245], v[104:105], 0, v[244:245]
	global_load_dwordx4 v[230:233], v[244:245], off offset:2048
	v_add_u32_e32 v246, s98, v161
	v_ashrrev_i32_e32 v247, 31, v246
	v_lshlrev_b64 v[246:247], 12, v[246:247]
	v_lshl_add_u64 v[246:247], v[104:105], 0, v[246:247]
	global_load_dwordx4 v[234:237], v[246:247], off offset:2048
	ds_bpermute_b32 v88, v122, v34
	ds_bpermute_b32 v220, v122, v35
	ds_bpermute_b32 v221, v157, v35
	s_waitcnt lgkmcnt(1)
	v_fmac_f32_e32 v220, 0, v88
	ds_bpermute_b32 v88, v157, v34
	s_waitcnt lgkmcnt(0)
	v_fmac_f32_e32 v221, v220, v88
	ds_bpermute_b32 v88, v158, v34
	ds_bpermute_b32 v220, v158, v35
	ds_bpermute_b32 v34, v123, v34
	ds_bpermute_b32 v35, v123, v35
	s_waitcnt lgkmcnt(2)
	v_fmac_f32_e32 v220, v221, v88
	s_waitcnt lgkmcnt(0)
	v_fmac_f32_e32 v35, v220, v34
	v_fmac_f32_e32 v218, v219, v35
	v_fmac_f32_e32 v216, v217, v35
	v_fmac_f32_e32 v214, v215, v35
	v_fmac_f32_e32 v212, v213, v35
	v_fmac_f32_e32 v210, v211, v35
	v_fmac_f32_e32 v208, v209, v35
	v_fmac_f32_e32 v206, v207, v35
	v_fmac_f32_e32 v107, v205, v35
	v_fmac_f32_e32 v174, v172, v218
	v_fmac_f32_e32 v184, v182, v216
	v_fmac_f32_e32 v79, v78, v214
	v_fmac_f32_e32 v71, v70, v212
	v_fmac_f32_e32 v63, v62, v210
	v_fmac_f32_e32 v52, v54, v208
	v_fmac_f32_e32 v47, v46, v206
	v_fmac_f32_e32 v36, v201, v107
	v_fmac_f32_e32 v179, v173, v174
	v_fmac_f32_e32 v189, v183, v184
	v_fmac_f32_e32 v191, v75, v79
	v_fmac_f32_e32 v193, v67, v71
	v_fmac_f32_e32 v195, v59, v63
	v_fmac_f32_e32 v197, v51, v52
	v_fmac_f32_e32 v199, v43, v47
	v_fmac_f32_e32 v204, v39, v36
	v_fmac_f32_e32 v178, v176, v179
	v_fmac_f32_e32 v188, v186, v189
	v_fmac_f32_e32 v81, v80, v191
	v_fmac_f32_e32 v73, v72, v193
	v_fmac_f32_e32 v65, v64, v195
	v_fmac_f32_e32 v57, v56, v197
	v_fmac_f32_e32 v49, v48, v199
	v_fmac_f32_e32 v203, v202, v204
	v_fmac_f32_e32 v180, v177, v178
	v_fmac_f32_e32 v190, v187, v188
	v_fmac_f32_e32 v192, v77, v81
	v_fmac_f32_e32 v194, v69, v73
	v_fmac_f32_e32 v196, v61, v65
	v_fmac_f32_e32 v198, v53, v57
	v_fmac_f32_e32 v200, v45, v49
	v_fmac_f32_e32 v37, v41, v203
	ds_write2_b32 v125, v174, v179 offset1:132
	ds_write2_b32 v175, v178, v180 offset0:8 offset1:140
	ds_write2_b32 v181, v184, v189 offset0:64 offset1:196
	ds_write2_b32 v185, v188, v190 offset0:72 offset1:204
	ds_write2_b32 v74, v79, v191 offset1:132
	ds_write2_b32 v76, v81, v192 offset0:8 offset1:140
	ds_write2_b32 v66, v71, v193 offset0:64 offset1:196
	ds_write2_b32 v68, v73, v194 offset0:72 offset1:204
	ds_write2_b32 v58, v63, v195 offset1:132
	ds_write2_b32 v60, v65, v196 offset0:8 offset1:140
	ds_write2_b32 v50, v52, v197 offset0:64 offset1:196
	ds_write2_b32 v55, v57, v198 offset0:72 offset1:204
	ds_write2_b32 v42, v47, v199 offset1:132
	ds_write2_b32 v44, v49, v200 offset0:8 offset1:140
	ds_write2_b32 v38, v36, v204 offset0:64 offset1:196
	ds_write2_b32 v40, v203, v37 offset0:72 offset1:204
	s_and_saveexec_b64 s[14:15], s[24:25]
	s_cbranch_execz .LBB0_406
	s_lshl_b64 s[24:25], s[22:23], 12
	s_add_u32 s24, s88, s24
	s_addc_u32 s25, s89, s25
	v_lshl_add_u64 v[34:35], v[84:85], 2, s[24:25]
	v_add_co_u32_e32 v34, vcc, 0x8300000, v34
	s_nop 1
	v_addc_co_u32_e32 v35, vcc, 0, v35, vcc
	global_store_dword v[34:35], v37, off
	s_branch .LBB0_406

.LBB0_1981:
	s_ashr_i32 s1, s0, 31
	s_lshl_b64 s[6:7], s[0:1], 12
	s_add_u32 s10, s62, s6
	s_addc_u32 s11, s63, s7
	s_lshl_b64 s[0:1], s[0:1], 11
	s_add_u32 s0, s76, s0
	s_addc_u32 s1, s77, s1
	s_add_i32 s5, s5, 34
	s_mul_hi_i32 s6, s5, 0x3000
	s_mulk_i32 s5, 0x3000
	s_add_u32 s5, s62, s5
	s_addc_u32 s7, s63, s6
	v_lshlrev_b32_e32 v0, 4, v2
	v_mov_b32_e32 v1, 0
	s_add_u32 s6, s5, 0x2000
	v_lshl_add_u64 v[6:7], s[10:11], 0, v[0:1]
	s_mov_b64 s[10:11], 0x18acc000
	s_mov_b32 s5, 0x18acc000
	s_addc_u32 s7, s7, 0
	v_lshl_add_u64 v[20:21], v[6:7], 0, s[10:11]
	v_add_co_u32_e32 v6, vcc, s5, v6
	v_lshlrev_b32_e32 v14, 3, v2
	global_load_dwordx4 v[2:5], v0, s[6:7]
	global_load_dwordx2 v[18:19], v14, s[0:1]
	v_addc_co_u32_e32 v7, vcc, 0, v7, vcc
	v_or_b32_e32 v54, 0x400, v0
	v_or_b32_e32 v55, 0x800, v0
	global_load_dwordx2 v[22:23], v[6:7], off sc1
	global_load_dwordx2 v[24:25], v[20:21], off offset:8 sc1
	global_load_dwordx2 v[26:27], v14, s[0:1] offset:512
	s_nop 0
	global_load_dwordx4 v[6:9], v54, s[6:7]
	global_load_dwordx2 v[28:29], v[20:21], off offset:1024 sc1
	global_load_dwordx2 v[30:31], v[20:21], off offset:1032 sc1
	global_load_dwordx2 v[32:33], v14, s[0:1] offset:1024
	global_load_dwordx4 v[10:13], v55, s[6:7]
	global_load_dwordx2 v[34:35], v[20:21], off offset:2048 sc1
	global_load_dwordx2 v[36:37], v[20:21], off offset:2056 sc1
	global_load_dwordx2 v[38:39], v14, s[0:1] offset:1536
	v_or_b32_e32 v56, 0xc00, v0
	global_load_dwordx4 v[14:17], v56, s[6:7]
	global_load_dwordx2 v[40:41], v[20:21], off offset:3072 sc1
	global_load_dwordx2 v[42:43], v[20:21], off offset:3080 sc1
	s_mov_b32 s0, 0x3fb504f3
	s_ashr_i32 s5, s4, 31
	s_waitcnt vmcnt(15)
	v_pk_add_f32 v[4:5], v[4:5], 1.0 op_sel_hi:[1,0]
	s_waitcnt vmcnt(14)
	v_lshlrev_b32_e32 v20, 16, v18
	v_and_b32_e32 v21, 0xffff0000, v18
	v_lshlrev_b32_e32 v18, 16, v19
	v_and_b32_e32 v19, 0xffff0000, v19
	v_pk_add_f32 v[2:3], v[2:3], 1.0 op_sel_hi:[1,0]
	s_waitcnt vmcnt(11)
	v_lshlrev_b32_e32 v44, 16, v26
	v_and_b32_e32 v45, 0xffff0000, v26
	v_lshlrev_b32_e32 v26, 16, v27
	v_and_b32_e32 v27, 0xffff0000, v27
	s_waitcnt vmcnt(6)
	v_pk_add_f32 v[48:49], v[12:13], 1.0 op_sel_hi:[1,0]
	s_waitcnt vmcnt(3)
	v_lshlrev_b32_e32 v12, 16, v39
	v_and_b32_e32 v13, 0xffff0000, v39
	v_pk_mul_f32 v[18:19], v[18:19], s[0:1] op_sel_hi:[1,0]
	v_pk_mul_f32 v[20:21], v[20:21], s[0:1] op_sel_hi:[1,0]
	v_pk_add_f32 v[8:9], v[8:9], 1.0 op_sel_hi:[1,0]
	v_pk_add_f32 v[6:7], v[6:7], 1.0 op_sel_hi:[1,0]
	v_lshlrev_b32_e32 v46, 16, v32
	v_and_b32_e32 v47, 0xffff0000, v32
	v_pk_add_f32 v[50:51], v[10:11], 1.0 op_sel_hi:[1,0]
	v_lshlrev_b32_e32 v10, 16, v38
	v_and_b32_e32 v11, 0xffff0000, v38
	s_waitcnt vmcnt(2)
	v_pk_add_f32 v[16:17], v[16:17], 1.0 op_sel_hi:[1,0]
	v_pk_mul_f32 v[38:39], v[44:45], s[0:1] op_sel_hi:[1,0]
	v_pk_mul_f32 v[26:27], v[26:27], s[0:1] op_sel_hi:[1,0]
	v_pk_mul_f32 v[52:53], v[12:13], s[0:1] op_sel_hi:[1,0]
	v_pk_fma_f32 v[22:23], v[2:3], v[22:23], v[20:21]
	v_pk_fma_f32 v[24:25], v[4:5], v[24:25], v[18:19]
	v_pk_mul_f32 v[44:45], v[46:47], s[0:1] op_sel_hi:[1,0]
	v_pk_mul_f32 v[46:47], v[10:11], s[0:1] op_sel_hi:[1,0]
	v_pk_fma_f32 v[12:13], v[8:9], v[30:31], v[26:27]
	v_pk_fma_f32 v[10:11], v[6:7], v[28:29], v[38:39]
	s_waitcnt vmcnt(0)
	v_pk_fma_f32 v[2:3], v[16:17], v[42:43], v[52:53]
	v_pk_mov_b32 v[4:5], v[22:23], v[24:25] op_sel:[1,0]
	v_mov_b32_e32 v16, v22
	v_mov_b32_e32 v17, v25
	v_lshlrev_b32_e32 v32, 16, v33
	v_and_b32_e32 v33, 0xffff0000, v33
	v_pk_mov_b32 v[18:19], v[10:11], v[12:13] op_sel:[1,0]
	v_mov_b32_e32 v20, v10
	v_mov_b32_e32 v21, v13
	v_pk_add_f32 v[4:5], v[4:5], v[16:17]
	v_pk_add_f32 v[14:15], v[14:15], 1.0 op_sel_hi:[1,0]
	v_pk_mul_f32 v[32:33], v[32:33], s[0:1] op_sel_hi:[1,0]
	v_pk_add_f32 v[16:17], v[18:19], v[20:21]
	v_add_f32_e32 v4, v4, v5
	v_pk_fma_f32 v[8:9], v[48:49], v[36:37], v[32:33]
	v_pk_fma_f32 v[6:7], v[50:51], v[34:35], v[44:45]
	v_pk_add_f32 v[16:17], v[16:17], v[16:17] op_sel:[0,1] op_sel_hi:[1,0]
	v_add_f32_e32 v18, 0, v4
	v_pk_fma_f32 v[4:5], v[14:15], v[40:41], v[46:47]
	v_add_f32_e32 v26, v6, v7
	v_add_f32_e32 v28, v8, v9
	v_mov_b32_e32 v19, v4
	v_mov_b32_e32 v17, v5
	v_mov_b32_e32 v27, v2
	v_mov_b32_e32 v29, v3
	v_pk_add_f32 v[14:15], v[18:19], v[16:17]
	v_pk_add_f32 v[16:17], v[26:27], v[28:29]
	s_mov_b32 s0, 0xf800000
	v_pk_add_f32 v[14:15], v[14:15], v[16:17]
	s_nop 0
	v_add_f32_e32 v14, v14, v15
	v_mbcnt_lo_u32_b32 v15, -1, 0
	v_mbcnt_hi_u32_b32 v15, -1, v15
	v_and_b32_e32 v16, 64, v15
	v_add_u32_e32 v16, 64, v16
	v_xor_b32_e32 v17, 1, v15
	v_cmp_lt_i32_e32 vcc, v17, v16
	s_nop 1
	v_cndmask_b32_e32 v17, v15, v17, vcc
	v_lshlrev_b32_e32 v26, 2, v17
	ds_bpermute_b32 v17, v26, v14
	s_waitcnt lgkmcnt(0)
	v_add_f32_e32 v14, v14, v17
	v_xor_b32_e32 v17, 2, v15
	v_cmp_lt_i32_e32 vcc, v17, v16
	s_nop 1
	v_cndmask_b32_e32 v17, v15, v17, vcc
	v_lshlrev_b32_e32 v27, 2, v17
	ds_bpermute_b32 v17, v27, v14
	s_waitcnt lgkmcnt(0)
	v_add_f32_e32 v14, v14, v17
	v_xor_b32_e32 v17, 4, v15
	v_cmp_lt_i32_e32 vcc, v17, v16
	s_nop 1
	v_cndmask_b32_e32 v17, v15, v17, vcc
	v_lshlrev_b32_e32 v28, 2, v17
	ds_bpermute_b32 v17, v28, v14
	s_waitcnt lgkmcnt(0)
	v_add_f32_e32 v14, v14, v17
	v_xor_b32_e32 v17, 8, v15
	v_cmp_lt_i32_e32 vcc, v17, v16
	s_nop 1
	v_cndmask_b32_e32 v17, v15, v17, vcc
	v_lshlrev_b32_e32 v29, 2, v17
	ds_bpermute_b32 v17, v29, v14
	s_waitcnt lgkmcnt(0)
	v_add_f32_e32 v14, v14, v17
	v_xor_b32_e32 v17, 16, v15
	v_cmp_lt_i32_e32 vcc, v17, v16
	s_nop 1
	v_cndmask_b32_e32 v17, v15, v17, vcc
	v_lshlrev_b32_e32 v30, 2, v17
	ds_bpermute_b32 v17, v30, v14
	s_waitcnt lgkmcnt(0)
	v_add_f32_e32 v14, v14, v17
	v_xor_b32_e32 v17, 32, v15
	v_cmp_lt_i32_e32 vcc, v17, v16
	s_nop 1
	v_cndmask_b32_e32 v15, v15, v17, vcc
	v_lshlrev_b32_e32 v31, 2, v15
	ds_bpermute_b32 v15, v31, v14
	s_waitcnt lgkmcnt(0)
	v_add_f32_e32 v32, v14, v15
	v_fmamk_f32 v23, v32, 0xba800000, v23
	v_fmac_f32_e32 v22, 0xba800000, v32
	v_fmamk_f32 v25, v32, 0xba800000, v25
	v_fmac_f32_e32 v24, 0xba800000, v32
	v_pk_mul_f32 v[14:15], v[24:25], v[24:25]
	v_pk_mul_f32 v[16:17], v[22:23], v[22:23]
	v_fmamk_f32 v11, v32, 0xba800000, v11
	v_pk_mov_b32 v[18:19], v[16:17], v[14:15] op_sel:[1,0]
	v_mov_b32_e32 v17, v15
	v_pk_add_f32 v[14:15], v[18:19], v[16:17]
	v_fmac_f32_e32 v10, 0xba800000, v32
	v_fmamk_f32 v13, v32, 0xba800000, v13
	v_fmac_f32_e32 v12, 0xba800000, v32
	v_pk_add_f32 v[14:15], v[14:15], v[14:15] op_sel_hi:[0,1]
	v_pk_mul_f32 v[16:17], v[12:13], v[12:13]
	v_pk_mul_f32 v[18:19], v[10:11], v[10:11]
	v_fmac_f32_e32 v6, 0xba800000, v32
	v_pk_mov_b32 v[20:21], v[18:19], v[16:17] op_sel:[1,0]
	v_mov_b32_e32 v19, v17
	v_fmamk_f32 v7, v32, 0xba800000, v7
	v_fmac_f32_e32 v8, 0xba800000, v32
	v_mul_f32_e32 v14, v6, v6
	v_pk_add_f32 v[16:17], v[20:21], v[18:19]
	v_fmamk_f32 v9, v32, 0xba800000, v9
	v_pk_fma_f32 v[18:19], v[6:7], v[6:7], v[14:15] op_sel_hi:[1,1,0]
	v_mul_f32_e32 v14, v8, v8
	v_pk_add_f32 v[16:17], v[16:17], v[16:17] op_sel_hi:[0,1]
	v_pk_fma_f32 v[20:21], v[8:9], v[8:9], v[14:15] op_sel_hi:[1,1,0]
	v_fmamk_f32 v3, v32, 0xba800000, v3
	v_fmac_f32_e32 v2, 0xba800000, v32
	v_fmamk_f32 v5, v32, 0xba800000, v5
	v_fmac_f32_e32 v4, 0xba800000, v32
	v_mul_f32_e32 v18, v4, v4
	v_mul_f32_e32 v20, v5, v5
	v_mul_f32_e32 v14, v2, v2
	v_mul_f32_e32 v16, v3, v3
	v_pk_add_f32 v[18:19], v[18:19], v[20:21]
	v_pk_add_f32 v[14:15], v[14:15], v[16:17]
	s_nop 0
	v_pk_add_f32 v[14:15], v[18:19], v[14:15]
	s_nop 0
	v_add_f32_e32 v32, v14, v15
	global_load_dwordx4 v[14:17], v0, s[2:3]
	global_load_dwordx4 v[18:21], v0, s[8:9]
	global_load_dwordx4 v[60:63], v54, s[2:3]
	global_load_dwordx4 v[64:67], v54, s[8:9]
	global_load_dwordx4 v[68:71], v55, s[2:3]
	global_load_dwordx4 v[72:75], v55, s[8:9]
	global_load_dwordx4 v[76:79], v56, s[2:3]
	global_load_dwordx4 v[80:83], v56, s[8:9]
	ds_bpermute_b32 v26, v26, v32
	s_waitcnt lgkmcnt(0)
	v_add_f32_e32 v26, v32, v26
	ds_bpermute_b32 v27, v27, v26
	s_waitcnt lgkmcnt(0)
	v_add_f32_e32 v26, v26, v27
	ds_bpermute_b32 v27, v28, v26
	s_waitcnt lgkmcnt(0)
	v_add_f32_e32 v26, v26, v27
	ds_bpermute_b32 v27, v29, v26
	s_waitcnt lgkmcnt(0)
	v_add_f32_e32 v26, v26, v27
	ds_bpermute_b32 v27, v30, v26
	s_waitcnt lgkmcnt(0)
	v_add_f32_e32 v26, v26, v27
	ds_bpermute_b32 v27, v31, v26
	s_waitcnt lgkmcnt(0)
	v_add_f32_e32 v26, v26, v27
	v_mov_b32_e32 v27, 0x3727c5ac
	v_fmac_f32_e32 v27, 0x3a800000, v26
	v_mul_f32_e32 v26, 0x4f800000, v27
	v_cmp_gt_f32_e32 vcc, s0, v27
	s_nop 1
	v_cndmask_b32_e32 v26, v27, v26, vcc
	v_sqrt_f32_e32 v27, v26
	s_nop 0
	v_add_u32_e32 v28, -1, v27
	v_fma_f32 v29, -v28, v27, v26
	v_cmp_ge_f32_e64 s[0:1], 0, v29
	v_add_u32_e32 v29, 1, v27
	s_nop 0
	v_cndmask_b32_e64 v28, v27, v28, s[0:1]
	v_fma_f32 v27, -v29, v27, v26
	v_cmp_lt_f32_e64 s[0:1], 0, v27
	s_nop 1
	v_cndmask_b32_e64 v27, v28, v29, s[0:1]
	v_mul_f32_e32 v28, 0x37800000, v27
	v_cndmask_b32_e32 v27, v27, v28, vcc
	v_mov_b32_e32 v28, 0x260
	v_cmp_class_f32_e32 vcc, v26, v28
	s_nop 1
	v_cndmask_b32_e32 v26, v27, v26, vcc
	v_div_scale_f32 v27, s[0:1], v26, v26, 1.0
	v_rcp_f32_e32 v28, v27
	s_lshl_b64 s[0:1], s[4:5], 12
	s_add_u32 s0, s60, s0
	s_addc_u32 s1, s61, s1
	v_fma_f32 v29, -v27, v28, 1.0
	v_fmac_f32_e32 v28, v29, v28
	v_div_scale_f32 v29, vcc, 1.0, v26, 1.0
	v_mul_f32_e32 v30, v29, v28
	v_fma_f32 v31, -v27, v30, v29
	v_fmac_f32_e32 v30, v31, v28
	v_fma_f32 v27, -v27, v30, v29
	v_div_fmas_f32 v27, v27, v28, v30
	v_div_fixup_f32 v26, v27, v26, 1.0
	v_pk_mul_f32 v[22:23], v[22:23], v[26:27] op_sel_hi:[1,0]
	v_lshl_add_u64 v[0:1], s[0:1], 0, v[0:1]
	s_brev_b32 s0, 32
	v_pk_mul_f32 v[24:25], v[24:25], v[26:27] op_sel_hi:[1,0]
	s_waitcnt vmcnt(0)
	v_pk_fma_f32 v[14:15], v[14:15], v[22:23], v[18:19]
	v_add_co_u32_e32 v18, vcc, s0, v0
	v_pk_fma_f32 v[16:17], v[16:17], v[24:25], v[20:21]
	s_nop 0
	v_addc_co_u32_e32 v19, vcc, 0, v1, vcc
	global_store_dwordx4 v[18:19], v[14:17], off
	s_mov_b64 s[0:1], 0x4000000
	v_lshl_add_u64 v[22:23], v[0:1], 0, s[0:1]
	v_pk_mul_f32 v[0:1], v[12:13], v[26:27] op_sel_hi:[1,0]
	v_pk_mul_f32 v[10:11], v[10:11], v[26:27] op_sel_hi:[1,0]
	v_pk_mul_f32 v[6:7], v[6:7], v[26:27] op_sel_hi:[1,0]
	v_pk_mul_f32 v[2:3], v[2:3], v[26:27] op_sel_hi:[1,0]
	v_pk_fma_f32 v[10:11], v[60:61], v[10:11], v[64:65]
	v_pk_fma_f32 v[12:13], v[62:63], v[0:1], v[66:67]
	global_store_dwordx4 v[22:23], v[10:13], off offset:1024
	v_pk_mul_f32 v[0:1], v[8:9], v[26:27] op_sel_hi:[1,0]
	v_pk_fma_f32 v[6:7], v[68:69], v[6:7], v[72:73]
	v_pk_fma_f32 v[8:9], v[70:71], v[0:1], v[74:75]
	global_store_dwordx4 v[22:23], v[6:9], off offset:2048
	v_pk_mul_f32 v[0:1], v[4:5], v[26:27] op_sel_hi:[1,0]
	v_pk_fma_f32 v[2:3], v[78:79], v[2:3], v[82:83]
	v_pk_fma_f32 v[0:1], v[76:77], v[0:1], v[80:81]
	global_store_dwordx4 v[22:23], v[0:3], off offset:3072
	s_endpgm
